# speedup vs baseline: 1.0008x; 1.0008x over previous
.LBB0_849:
	v_lshl_or_b32 v158, s30, 8, v164
	v_readlane_b32 s0, v253, 50
	v_ashrrev_i32_e32 v159, 31, v158
	v_readlane_b32 s1, v253, 51
	v_lshl_add_u32 v160, s29, 8, v162
	v_ashrrev_i32_e32 v161, 31, v160
	v_lshl_add_u64 v[156:157], v[158:159], 2, s[0:1]
	global_load_dwordx4 v[140:143], v[156:157], off offset:16
	global_load_dwordx4 v[144:147], v[156:157], off
	v_lshl_add_u32 v184, v160, 11, v158
	v_lshlrev_b32_e32 v184, 2, v184
	v_readlane_b32 s100, v253, 58
	v_readlane_b32 s101, v253, 59
	s_nop 1
	s_add_u32 s100, s100, 0x0
	s_addc_u32 s101, s101, 0
	global_load_dwordx4 v[176:179], v184, s[100:101] offset:16
	global_load_dwordx4 v[180:183], v184, s[100:101] offset:0
	global_load_dwordx4 v[188:191], v184, s[100:101] offset:528
	global_load_dwordx4 v[192:195], v184, s[100:101] offset:512
	s_add_u32 s100, s100, 0x20000
	s_addc_u32 s101, s101, 0
	global_load_dwordx4 v[196:199], v184, s[100:101] offset:16
	global_load_dwordx4 v[200:203], v184, s[100:101] offset:0
	global_load_dwordx4 v[204:207], v184, s[100:101] offset:528
	global_load_dwordx4 v[218:221], v184, s[100:101] offset:512
	v_readlane_b32 s0, v253, 58
	v_readlane_b32 s1, v253, 59
	s_mov_b64 s[18:19], 0x40000
	s_andn2_b64 vcc, exec, s[4:5]
	s_mov_b32 s44, 0x8000
	s_mov_b32 s45, 0xa000
	s_waitcnt vmcnt(0)
	v_pk_add_f32 v[148:149], v[142:143], 1.0 op_sel_hi:[1,0]
	v_pk_add_f32 v[150:151], v[140:141], 1.0 op_sel_hi:[1,0]
	global_load_dwordx4 v[166:169], v[156:157], off offset:528
	global_load_dwordx4 v[140:143], v[156:157], off offset:512
	v_lshlrev_b64 v[156:157], 11, v[160:161]
	v_lshl_add_u64 v[156:157], v[156:157], 0, v[158:159]
	v_lshl_add_u64 v[174:175], v[156:157], 2, s[0:1]
	v_pk_add_f32 v[152:153], v[146:147], 1.0 op_sel_hi:[1,0]
	v_pk_add_f32 v[154:155], v[144:145], 1.0 op_sel_hi:[1,0]
	s_waitcnt vmcnt(0)
	v_pk_add_f32 v[144:145], v[142:143], 1.0 op_sel_hi:[1,0]
	v_pk_add_f32 v[146:147], v[140:141], 1.0 op_sel_hi:[1,0]
	v_pk_add_f32 v[140:141], v[168:169], 1.0 op_sel_hi:[1,0]
	v_pk_add_f32 v[142:143], v[166:167], 1.0 op_sel_hi:[1,0]
	v_pk_mul_f32 v[168:169], v[178:179], s[60:61] op_sel_hi:[1,0]
	v_pk_mul_f32 v[172:173], v[182:183], s[60:61] op_sel_hi:[1,0]
	v_pk_mul_f32 v[170:171], v[180:181], s[60:61] op_sel_hi:[1,0]
	v_pk_mul_f32 v[166:167], v[176:177], s[60:61] op_sel_hi:[1,0]
	v_pk_fma_f32 v[128:129], v[128:129], v[152:153], v[172:173]
	v_pk_fma_f32 v[126:127], v[126:127], v[154:155], v[170:171]
	v_pk_fma_f32 v[168:169], v[124:125], v[148:149], v[168:169]
	v_pk_fma_f32 v[124:125], v[122:123], v[150:151], v[166:167]
	v_lshlrev_b64 v[166:167], 1, v[156:157]
	v_cvt_pk_bf16_f32 v122, v126, v127
	v_cvt_pk_bf16_f32 v123, v128, v129
	v_cvt_pk_bf16_f32 v124, v124, v125
	v_cvt_pk_bf16_f32 v125, v168, v169
	v_lshl_add_u64 v[126:127], s[50:51], 0, v[166:167]
	global_store_dwordx4 v[126:127], v[122:125], off
	s_nop 0
	v_or_b32_e32 v166, 0x100, v166
	v_pk_mul_f32 v[124:125], v[190:191], s[60:61] op_sel_hi:[1,0]
	v_pk_mul_f32 v[128:129], v[194:195], s[60:61] op_sel_hi:[1,0]
	v_pk_mul_f32 v[126:127], v[192:193], s[60:61] op_sel_hi:[1,0]
	v_pk_mul_f32 v[122:123], v[188:189], s[60:61] op_sel_hi:[1,0]
	v_pk_fma_f32 v[120:121], v[120:121], v[144:145], v[128:129]
	v_pk_fma_f32 v[118:119], v[118:119], v[146:147], v[126:127]
	v_pk_fma_f32 v[124:125], v[116:117], v[140:141], v[124:125]
	v_pk_fma_f32 v[116:117], v[114:115], v[142:143], v[122:123]
	v_cvt_pk_bf16_f32 v114, v118, v119
	v_cvt_pk_bf16_f32 v115, v120, v121
	v_cvt_pk_bf16_f32 v116, v116, v117
	v_cvt_pk_bf16_f32 v117, v124, v125
	v_lshl_add_u64 v[118:119], s[50:51], 0, v[166:167]
	global_store_dwordx4 v[118:119], v[114:117], off
	s_nop 1
	v_or_b32_e32 v114, 16, v160
	v_ashrrev_i32_e32 v115, 31, v114
	v_lshlrev_b64 v[114:115], 11, v[114:115]
	v_lshl_add_u64 v[122:123], v[114:115], 0, v[158:159]
	v_lshl_add_u64 v[124:125], v[122:123], 2, s[0:1]
	v_pk_mul_f32 v[116:117], v[198:199], s[60:61] op_sel_hi:[1,0]
	v_pk_mul_f32 v[120:121], v[202:203], s[60:61] op_sel_hi:[1,0]
	v_pk_mul_f32 v[118:119], v[200:201], s[60:61] op_sel_hi:[1,0]
	v_pk_mul_f32 v[114:115], v[196:197], s[60:61] op_sel_hi:[1,0]
	v_pk_fma_f32 v[112:113], v[112:113], v[152:153], v[120:121]
	v_pk_fma_f32 v[110:111], v[110:111], v[154:155], v[118:119]
	v_pk_fma_f32 v[116:117], v[108:109], v[148:149], v[116:117]
	v_pk_fma_f32 v[108:109], v[106:107], v[150:151], v[114:115]
	v_lshlrev_b64 v[114:115], 1, v[122:123]
	v_cvt_pk_bf16_f32 v106, v110, v111
	v_cvt_pk_bf16_f32 v107, v112, v113
	v_cvt_pk_bf16_f32 v108, v108, v109
	v_cvt_pk_bf16_f32 v109, v116, v117
	v_lshl_add_u64 v[110:111], s[50:51], 0, v[114:115]
	global_store_dwordx4 v[110:111], v[106:109], off
	s_nop 0
	v_or_b32_e32 v114, 0x100, v114
	v_pk_mul_f32 v[108:109], v[206:207], s[60:61] op_sel_hi:[1,0]
	v_pk_mul_f32 v[112:113], v[220:221], s[60:61] op_sel_hi:[1,0]
	v_pk_mul_f32 v[110:111], v[218:219], s[60:61] op_sel_hi:[1,0]
	v_pk_mul_f32 v[106:107], v[204:205], s[60:61] op_sel_hi:[1,0]
	v_pk_fma_f32 v[104:105], v[104:105], v[144:145], v[112:113]
	v_pk_fma_f32 v[102:103], v[102:103], v[146:147], v[110:111]
	v_pk_fma_f32 v[108:109], v[100:101], v[140:141], v[108:109]
	v_pk_fma_f32 v[100:101], v[98:99], v[142:143], v[106:107]
	v_cvt_pk_bf16_f32 v98, v102, v103
	v_cvt_pk_bf16_f32 v99, v104, v105
	v_cvt_pk_bf16_f32 v100, v100, v101
	v_cvt_pk_bf16_f32 v101, v108, v109
	v_lshl_add_u64 v[102:103], s[50:51], 0, v[114:115]
	global_store_dwordx4 v[102:103], v[98:101], off
	s_nop 1
	v_or_b32_e32 v98, 32, v160
	v_ashrrev_i32_e32 v99, 31, v98
	v_lshlrev_b64 v[98:99], 11, v[98:99]
	v_lshl_add_u64 v[106:107], v[98:99], 0, v[158:159]
	v_lshl_add_u64 v[108:109], v[106:107], 2, s[0:1]
	v_lshlrev_b32_e32 v184, 2, v156
	v_readlane_b32 s100, v253, 58
	v_readlane_b32 s101, v253, 59
	s_nop 1
	s_add_u32 s100, s100, 0x40000
	s_addc_u32 s101, s101, 0
	global_load_dwordx4 v[176:179], v184, s[100:101] offset:16
	global_load_dwordx4 v[180:183], v184, s[100:101] offset:0
	global_load_dwordx4 v[188:191], v184, s[100:101] offset:528
	global_load_dwordx4 v[192:195], v184, s[100:101] offset:512
	s_add_u32 s100, s100, 0x20000
	s_addc_u32 s101, s101, 0
	global_load_dwordx4 v[196:199], v184, s[100:101] offset:16
	global_load_dwordx4 v[200:203], v184, s[100:101] offset:0
	global_load_dwordx4 v[204:207], v184, s[100:101] offset:528
	global_load_dwordx4 v[218:221], v184, s[100:101] offset:512
	s_waitcnt vmcnt(0)
	v_pk_mul_f32 v[100:101], v[178:179], s[60:61] op_sel_hi:[1,0]
	v_pk_mul_f32 v[104:105], v[182:183], s[60:61] op_sel_hi:[1,0]
	v_pk_mul_f32 v[102:103], v[180:181], s[60:61] op_sel_hi:[1,0]
	v_pk_mul_f32 v[98:99], v[176:177], s[60:61] op_sel_hi:[1,0]
	v_pk_fma_f32 v[96:97], v[96:97], v[152:153], v[104:105]
	v_pk_fma_f32 v[94:95], v[94:95], v[154:155], v[102:103]
	v_pk_fma_f32 v[100:101], v[92:93], v[148:149], v[100:101]
	v_pk_fma_f32 v[92:93], v[90:91], v[150:151], v[98:99]
	v_lshlrev_b64 v[98:99], 1, v[106:107]
	v_cvt_pk_bf16_f32 v90, v94, v95
	v_cvt_pk_bf16_f32 v91, v96, v97
	v_cvt_pk_bf16_f32 v92, v92, v93
	v_cvt_pk_bf16_f32 v93, v100, v101
	v_lshl_add_u64 v[94:95], s[50:51], 0, v[98:99]
	global_store_dwordx4 v[94:95], v[90:93], off
	s_nop 0
	v_or_b32_e32 v98, 0x100, v98
	v_pk_mul_f32 v[92:93], v[190:191], s[60:61] op_sel_hi:[1,0]
	v_pk_mul_f32 v[96:97], v[194:195], s[60:61] op_sel_hi:[1,0]
	v_pk_mul_f32 v[94:95], v[192:193], s[60:61] op_sel_hi:[1,0]
	v_pk_mul_f32 v[90:91], v[188:189], s[60:61] op_sel_hi:[1,0]
	v_pk_fma_f32 v[88:89], v[88:89], v[144:145], v[96:97]
	v_pk_fma_f32 v[86:87], v[86:87], v[146:147], v[94:95]
	v_pk_fma_f32 v[92:93], v[84:85], v[140:141], v[92:93]
	v_pk_fma_f32 v[84:85], v[82:83], v[142:143], v[90:91]
	v_cvt_pk_bf16_f32 v82, v86, v87
	v_cvt_pk_bf16_f32 v83, v88, v89
	v_cvt_pk_bf16_f32 v84, v84, v85
	v_cvt_pk_bf16_f32 v85, v92, v93
	v_lshl_add_u64 v[86:87], s[50:51], 0, v[98:99]
	global_store_dwordx4 v[86:87], v[82:85], off
	s_nop 1
	v_or_b32_e32 v82, 48, v160
	v_ashrrev_i32_e32 v83, 31, v82
	v_lshlrev_b64 v[82:83], 11, v[82:83]
	v_lshl_add_u64 v[90:91], v[82:83], 0, v[158:159]
	v_lshl_add_u64 v[92:93], v[90:91], 2, s[0:1]
	v_pk_mul_f32 v[84:85], v[198:199], s[60:61] op_sel_hi:[1,0]
	v_pk_mul_f32 v[88:89], v[202:203], s[60:61] op_sel_hi:[1,0]
	v_pk_mul_f32 v[86:87], v[200:201], s[60:61] op_sel_hi:[1,0]
	v_pk_mul_f32 v[82:83], v[196:197], s[60:61] op_sel_hi:[1,0]
	v_pk_fma_f32 v[80:81], v[80:81], v[152:153], v[88:89]
	v_pk_fma_f32 v[78:79], v[78:79], v[154:155], v[86:87]
	v_pk_fma_f32 v[84:85], v[76:77], v[148:149], v[84:85]
	v_pk_fma_f32 v[76:77], v[74:75], v[150:151], v[82:83]
	v_lshlrev_b64 v[82:83], 1, v[90:91]
	v_cvt_pk_bf16_f32 v74, v78, v79
	v_cvt_pk_bf16_f32 v75, v80, v81
	v_cvt_pk_bf16_f32 v76, v76, v77
	v_cvt_pk_bf16_f32 v77, v84, v85
	v_lshl_add_u64 v[78:79], s[50:51], 0, v[82:83]
	global_store_dwordx4 v[78:79], v[74:77], off
	s_nop 0
	v_or_b32_e32 v82, 0x100, v82
	v_pk_mul_f32 v[76:77], v[206:207], s[60:61] op_sel_hi:[1,0]
	v_pk_mul_f32 v[80:81], v[220:221], s[60:61] op_sel_hi:[1,0]
	v_pk_mul_f32 v[78:79], v[218:219], s[60:61] op_sel_hi:[1,0]
	v_pk_mul_f32 v[74:75], v[204:205], s[60:61] op_sel_hi:[1,0]
	v_pk_fma_f32 v[72:73], v[72:73], v[144:145], v[80:81]
	v_pk_fma_f32 v[70:71], v[70:71], v[146:147], v[78:79]
	v_pk_fma_f32 v[76:77], v[68:69], v[140:141], v[76:77]
	v_pk_fma_f32 v[68:69], v[66:67], v[142:143], v[74:75]
	v_cvt_pk_bf16_f32 v66, v70, v71
	v_cvt_pk_bf16_f32 v67, v72, v73
	v_cvt_pk_bf16_f32 v68, v68, v69
	v_cvt_pk_bf16_f32 v69, v76, v77
	v_lshl_add_u64 v[70:71], s[50:51], 0, v[82:83]
	v_lshl_add_u64 v[74:75], v[156:157], 0, s[18:19]
	global_store_dwordx4 v[70:71], v[66:69], off
	v_lshl_add_u64 v[76:77], v[74:75], 2, s[0:1]
	v_lshlrev_b32_e32 v184, 2, v156
	v_readlane_b32 s100, v253, 58
	v_readlane_b32 s101, v253, 59
	s_nop 1
	s_add_u32 s100, s100, 0x100000
	s_addc_u32 s101, s101, 0
	global_load_dwordx4 v[176:179], v184, s[100:101] offset:16
	global_load_dwordx4 v[180:183], v184, s[100:101] offset:0
	global_load_dwordx4 v[188:191], v184, s[100:101] offset:528
	global_load_dwordx4 v[192:195], v184, s[100:101] offset:512
	s_add_u32 s100, s100, 0x20000
	s_addc_u32 s101, s101, 0
	global_load_dwordx4 v[196:199], v184, s[100:101] offset:16
	global_load_dwordx4 v[200:203], v184, s[100:101] offset:0
	global_load_dwordx4 v[204:207], v184, s[100:101] offset:528
	global_load_dwordx4 v[218:221], v184, s[100:101] offset:512
	s_waitcnt vmcnt(0)
	s_mov_b64 s[18:19], 0x48000
	v_pk_mul_f32 v[68:69], v[178:179], s[60:61] op_sel_hi:[1,0]
	v_pk_mul_f32 v[72:73], v[182:183], s[60:61] op_sel_hi:[1,0]
	v_pk_mul_f32 v[70:71], v[180:181], s[60:61] op_sel_hi:[1,0]
	v_pk_mul_f32 v[66:67], v[176:177], s[60:61] op_sel_hi:[1,0]
	v_pk_fma_f32 v[64:65], v[64:65], v[152:153], v[72:73]
	v_pk_fma_f32 v[62:63], v[62:63], v[154:155], v[70:71]
	v_pk_fma_f32 v[68:69], v[60:61], v[148:149], v[68:69]
	v_pk_fma_f32 v[60:61], v[58:59], v[150:151], v[66:67]
	v_lshlrev_b64 v[66:67], 1, v[74:75]
	v_cvt_pk_bf16_f32 v58, v62, v63
	v_cvt_pk_bf16_f32 v59, v64, v65
	v_cvt_pk_bf16_f32 v60, v60, v61
	v_cvt_pk_bf16_f32 v61, v68, v69
	v_lshl_add_u64 v[62:63], s[50:51], 0, v[66:67]
	global_store_dwordx4 v[62:63], v[58:61], off
	s_nop 0
	v_or_b32_e32 v66, 0x100, v66
	v_pk_mul_f32 v[60:61], v[190:191], s[60:61] op_sel_hi:[1,0]
	v_pk_mul_f32 v[64:65], v[194:195], s[60:61] op_sel_hi:[1,0]
	v_pk_mul_f32 v[62:63], v[192:193], s[60:61] op_sel_hi:[1,0]
	v_pk_mul_f32 v[58:59], v[188:189], s[60:61] op_sel_hi:[1,0]
	v_pk_fma_f32 v[56:57], v[56:57], v[144:145], v[64:65]
	v_pk_fma_f32 v[54:55], v[54:55], v[146:147], v[62:63]
	v_pk_fma_f32 v[60:61], v[52:53], v[140:141], v[60:61]
	v_pk_fma_f32 v[52:53], v[50:51], v[142:143], v[58:59]
	v_cvt_pk_bf16_f32 v50, v54, v55
	v_cvt_pk_bf16_f32 v51, v56, v57
	v_cvt_pk_bf16_f32 v52, v52, v53
	v_cvt_pk_bf16_f32 v53, v60, v61
	v_lshl_add_u64 v[54:55], s[50:51], 0, v[66:67]
	v_lshl_add_u64 v[58:59], v[156:157], 0, s[18:19]
	global_store_dwordx4 v[54:55], v[50:53], off
	v_lshl_add_u64 v[60:61], v[58:59], 2, s[0:1]
	s_mov_b64 s[18:19], 0x50000
	v_pk_mul_f32 v[52:53], v[198:199], s[60:61] op_sel_hi:[1,0]
	v_pk_mul_f32 v[56:57], v[202:203], s[60:61] op_sel_hi:[1,0]
	v_pk_mul_f32 v[54:55], v[200:201], s[60:61] op_sel_hi:[1,0]
	v_pk_mul_f32 v[50:51], v[196:197], s[60:61] op_sel_hi:[1,0]
	v_pk_fma_f32 v[48:49], v[48:49], v[152:153], v[56:57]
	v_pk_fma_f32 v[46:47], v[46:47], v[154:155], v[54:55]
	v_pk_fma_f32 v[52:53], v[44:45], v[148:149], v[52:53]
	v_pk_fma_f32 v[44:45], v[42:43], v[150:151], v[50:51]
	v_lshlrev_b64 v[50:51], 1, v[58:59]
	v_cvt_pk_bf16_f32 v42, v46, v47
	v_cvt_pk_bf16_f32 v43, v48, v49
	v_cvt_pk_bf16_f32 v44, v44, v45
	v_cvt_pk_bf16_f32 v45, v52, v53
	v_lshl_add_u64 v[46:47], s[50:51], 0, v[50:51]
	global_store_dwordx4 v[46:47], v[42:45], off
	s_nop 0
	v_or_b32_e32 v50, 0x100, v50
	v_pk_mul_f32 v[44:45], v[206:207], s[60:61] op_sel_hi:[1,0]
	v_pk_mul_f32 v[48:49], v[220:221], s[60:61] op_sel_hi:[1,0]
	v_pk_mul_f32 v[46:47], v[218:219], s[60:61] op_sel_hi:[1,0]
	v_pk_mul_f32 v[42:43], v[204:205], s[60:61] op_sel_hi:[1,0]
	v_pk_fma_f32 v[40:41], v[40:41], v[144:145], v[48:49]
	v_pk_fma_f32 v[38:39], v[38:39], v[146:147], v[46:47]
	v_pk_fma_f32 v[44:45], v[36:37], v[140:141], v[44:45]
	v_pk_fma_f32 v[36:37], v[34:35], v[142:143], v[42:43]
	v_cvt_pk_bf16_f32 v34, v38, v39
	v_cvt_pk_bf16_f32 v35, v40, v41
	v_cvt_pk_bf16_f32 v36, v36, v37
	v_cvt_pk_bf16_f32 v37, v44, v45
	v_lshl_add_u64 v[38:39], s[50:51], 0, v[50:51]
	v_lshl_add_u64 v[42:43], v[156:157], 0, s[18:19]
	global_store_dwordx4 v[38:39], v[34:37], off
	v_lshl_add_u64 v[44:45], v[42:43], 2, s[0:1]
	v_lshlrev_b32_e32 v184, 2, v156
	v_readlane_b32 s100, v253, 58
	v_readlane_b32 s101, v253, 59
	s_nop 1
	s_add_u32 s100, s100, 0x140000
	s_addc_u32 s101, s101, 0
	global_load_dwordx4 v[176:179], v184, s[100:101] offset:16
	global_load_dwordx4 v[180:183], v184, s[100:101] offset:0
	global_load_dwordx4 v[188:191], v184, s[100:101] offset:528
	global_load_dwordx4 v[192:195], v184, s[100:101] offset:512
	s_add_u32 s100, s100, 0x20000
	s_addc_u32 s101, s101, 0
	global_load_dwordx4 v[196:199], v184, s[100:101] offset:16
	global_load_dwordx4 v[200:203], v184, s[100:101] offset:0
	global_load_dwordx4 v[204:207], v184, s[100:101] offset:528
	global_load_dwordx4 v[218:221], v184, s[100:101] offset:512
	s_waitcnt vmcnt(0)
	s_mov_b64 s[18:19], 0x58000
	v_pk_mul_f32 v[36:37], v[178:179], s[60:61] op_sel_hi:[1,0]
	v_pk_mul_f32 v[40:41], v[182:183], s[60:61] op_sel_hi:[1,0]
	v_pk_mul_f32 v[38:39], v[180:181], s[60:61] op_sel_hi:[1,0]
	v_pk_mul_f32 v[34:35], v[176:177], s[60:61] op_sel_hi:[1,0]
	v_pk_fma_f32 v[32:33], v[32:33], v[152:153], v[40:41]
	v_pk_fma_f32 v[30:31], v[30:31], v[154:155], v[38:39]
	v_pk_fma_f32 v[36:37], v[28:29], v[148:149], v[36:37]
	v_pk_fma_f32 v[28:29], v[26:27], v[150:151], v[34:35]
	v_lshlrev_b64 v[34:35], 1, v[42:43]
	v_cvt_pk_bf16_f32 v26, v30, v31
	v_cvt_pk_bf16_f32 v27, v32, v33
	v_cvt_pk_bf16_f32 v28, v28, v29
	v_cvt_pk_bf16_f32 v29, v36, v37
	v_lshl_add_u64 v[30:31], s[50:51], 0, v[34:35]
	global_store_dwordx4 v[30:31], v[26:29], off
	s_nop 0
	v_or_b32_e32 v34, 0x100, v34
	v_pk_mul_f32 v[28:29], v[190:191], s[60:61] op_sel_hi:[1,0]
	v_pk_mul_f32 v[32:33], v[194:195], s[60:61] op_sel_hi:[1,0]
	v_pk_mul_f32 v[30:31], v[192:193], s[60:61] op_sel_hi:[1,0]
	v_pk_mul_f32 v[26:27], v[188:189], s[60:61] op_sel_hi:[1,0]
	v_pk_fma_f32 v[24:25], v[24:25], v[144:145], v[32:33]
	v_pk_fma_f32 v[22:23], v[22:23], v[146:147], v[30:31]
	v_pk_fma_f32 v[28:29], v[20:21], v[140:141], v[28:29]
	v_pk_fma_f32 v[20:21], v[18:19], v[142:143], v[26:27]
	v_cvt_pk_bf16_f32 v18, v22, v23
	v_cvt_pk_bf16_f32 v19, v24, v25
	v_cvt_pk_bf16_f32 v20, v20, v21
	v_cvt_pk_bf16_f32 v21, v28, v29
	v_lshl_add_u64 v[22:23], s[50:51], 0, v[34:35]
	v_lshl_add_u64 v[26:27], v[156:157], 0, s[18:19]
	global_store_dwordx4 v[22:23], v[18:21], off
	v_lshl_add_u64 v[28:29], v[26:27], 2, s[0:1]
	s_mov_b64 s[0:1], -1
	v_pk_mul_f32 v[20:21], v[198:199], s[60:61] op_sel_hi:[1,0]
	v_pk_mul_f32 v[24:25], v[202:203], s[60:61] op_sel_hi:[1,0]
	v_pk_mul_f32 v[22:23], v[200:201], s[60:61] op_sel_hi:[1,0]
	v_pk_mul_f32 v[18:19], v[196:197], s[60:61] op_sel_hi:[1,0]
	v_pk_fma_f32 v[16:17], v[16:17], v[152:153], v[24:25]
	v_pk_fma_f32 v[14:15], v[14:15], v[154:155], v[22:23]
	v_pk_fma_f32 v[20:21], v[12:13], v[148:149], v[20:21]
	v_pk_fma_f32 v[12:13], v[10:11], v[150:151], v[18:19]
	v_lshlrev_b64 v[18:19], 1, v[26:27]
	v_cvt_pk_bf16_f32 v10, v14, v15
	v_cvt_pk_bf16_f32 v11, v16, v17
	v_cvt_pk_bf16_f32 v12, v12, v13
	v_cvt_pk_bf16_f32 v13, v20, v21
	v_lshl_add_u64 v[14:15], s[50:51], 0, v[18:19]
	global_store_dwordx4 v[14:15], v[10:13], off
	s_nop 0
	v_or_b32_e32 v18, 0x100, v18
	v_pk_mul_f32 v[12:13], v[206:207], s[60:61] op_sel_hi:[1,0]
	v_pk_mul_f32 v[16:17], v[220:221], s[60:61] op_sel_hi:[1,0]
	v_pk_mul_f32 v[14:15], v[218:219], s[60:61] op_sel_hi:[1,0]
	v_pk_mul_f32 v[10:11], v[204:205], s[60:61] op_sel_hi:[1,0]
	v_pk_fma_f32 v[8:9], v[8:9], v[144:145], v[16:17]
	v_pk_fma_f32 v[6:7], v[6:7], v[146:147], v[14:15]
	v_pk_fma_f32 v[12:13], v[4:5], v[140:141], v[12:13]
	v_pk_fma_f32 v[4:5], v[2:3], v[142:143], v[10:11]
	v_cvt_pk_bf16_f32 v2, v6, v7
	v_cvt_pk_bf16_f32 v3, v8, v9
	v_cvt_pk_bf16_f32 v4, v4, v5
	v_cvt_pk_bf16_f32 v5, v12, v13
	v_lshl_add_u64 v[6:7], s[50:51], 0, v[18:19]
	global_store_dwordx4 v[6:7], v[2:5], off
	s_cbranch_vccnz .LBB0_838
	s_andn2_b64 vcc, exec, s[6:7]
	s_cbranch_vccnz .LBB0_837
	s_barrier
	s_branch .LBB0_837

.LBB0_1027:
	v_lshl_or_b32 v158, s44, 8, v164
	v_ashrrev_i32_e32 v159, 31, v158
	v_lshl_add_u64 v[156:157], v[158:159], 2, s[6:7]
	global_load_dwordx4 v[140:143], v[156:157], off offset:16
	global_load_dwordx4 v[144:147], v[156:157], off
	v_lshl_add_u32 v160, s41, 8, v162
	v_ashrrev_i32_e32 v161, 31, v160
	v_lshl_add_u32 v184, v160, 11, v158
	v_lshlrev_b32_e32 v184, 1, v184
	s_add_u32 s100, s50, 0x0
	s_addc_u32 s101, s51, 0
	global_load_dwordx4 v[176:179], v184, s[100:101]
	global_load_dwordx4 v[180:183], v184, s[100:101] offset:256
	s_add_u32 s100, s100, 0x10000
	s_addc_u32 s101, s101, 0
	global_load_dwordx4 v[188:191], v184, s[100:101]
	global_load_dwordx4 v[192:195], v184, s[100:101] offset:256
	s_add_u32 s100, s100, 0x10000
	s_addc_u32 s101, s101, 0
	global_load_dwordx4 v[196:199], v184, s[100:101]
	global_load_dwordx4 v[200:203], v184, s[100:101] offset:256
	s_add_u32 s100, s100, 0x10000
	s_addc_u32 s101, s101, 0
	global_load_dwordx4 v[204:207], v184, s[100:101]
	global_load_dwordx4 v[218:221], v184, s[100:101] offset:256
	s_mov_b64 s[20:21], 0x40000
	s_andn2_b64 vcc, exec, s[4:5]
	s_mov_b32 s42, 0xc000
	s_waitcnt vmcnt(0)
	v_pk_add_f32 v[148:149], v[142:143], 1.0 op_sel_hi:[1,0]
	v_pk_add_f32 v[150:151], v[140:141], 1.0 op_sel_hi:[1,0]
	global_load_dwordx4 v[166:169], v[156:157], off offset:528
	global_load_dwordx4 v[140:143], v[156:157], off offset:512
	v_lshlrev_b64 v[156:157], 11, v[160:161]
	v_lshl_add_u64 v[156:157], v[156:157], 0, v[158:159]
	v_lshlrev_b64 v[170:171], 1, v[156:157]
	v_pk_add_f32 v[154:155], v[144:145], 1.0 op_sel_hi:[1,0]
	v_pk_add_f32 v[152:153], v[146:147], 1.0 op_sel_hi:[1,0]
	s_waitcnt vmcnt(0)
	v_pk_add_f32 v[144:145], v[142:143], 1.0 op_sel_hi:[1,0]
	v_pk_add_f32 v[142:143], v[166:167], 1.0 op_sel_hi:[1,0]
	v_lshl_add_u64 v[166:167], s[50:51], 0, v[170:171]
	v_pk_add_f32 v[146:147], v[140:141], 1.0 op_sel_hi:[1,0]
	v_pk_add_f32 v[140:141], v[168:169], 1.0 op_sel_hi:[1,0]
	v_or_b32_e32 v170, 0x100, v170
	v_lshlrev_b32_e32 v172, 16, v176
	v_and_b32_e32 v173, 0xffff0000, v176
	v_lshlrev_b32_e32 v166, 16, v177
	v_and_b32_e32 v167, 0xffff0000, v177
	v_lshlrev_b32_e32 v174, 16, v178
	v_and_b32_e32 v175, 0xffff0000, v178
	v_pk_mul_f32 v[166:167], v[166:167], s[60:61] op_sel_hi:[1,0]
	v_lshlrev_b32_e32 v168, 16, v179
	v_and_b32_e32 v169, 0xffff0000, v179
	v_pk_mul_f32 v[172:173], v[172:173], s[60:61] op_sel_hi:[1,0]
	v_pk_fma_f32 v[128:129], v[128:129], v[152:153], v[166:167]
	v_pk_mul_f32 v[166:167], v[174:175], s[60:61] op_sel_hi:[1,0]
	v_pk_fma_f32 v[126:127], v[126:127], v[154:155], v[172:173]
	v_pk_mul_f32 v[168:169], v[168:169], s[60:61] op_sel_hi:[1,0]
	v_pk_fma_f32 v[122:123], v[122:123], v[150:151], v[166:167]
	v_lshl_add_u64 v[166:167], v[156:157], 2, s[36:37]
	v_pk_fma_f32 v[124:125], v[124:125], v[148:149], v[168:169]
	global_store_dwordx4 v[166:167], v[126:129], off
	global_store_dwordx4 v[166:167], v[122:125], off offset:16
	s_nop 1
	v_lshl_add_u64 v[122:123], s[50:51], 0, v[170:171]
	v_lshlrev_b32_e32 v126, 16, v180
	v_and_b32_e32 v127, 0xffff0000, v180
	v_lshlrev_b32_e32 v122, 16, v181
	v_and_b32_e32 v123, 0xffff0000, v181
	v_lshlrev_b32_e32 v128, 16, v182
	v_and_b32_e32 v129, 0xffff0000, v182
	v_pk_mul_f32 v[122:123], v[122:123], s[60:61] op_sel_hi:[1,0]
	v_lshlrev_b32_e32 v124, 16, v183
	v_and_b32_e32 v125, 0xffff0000, v183
	v_pk_mul_f32 v[126:127], v[126:127], s[60:61] op_sel_hi:[1,0]
	v_pk_fma_f32 v[120:121], v[120:121], v[144:145], v[122:123]
	v_pk_mul_f32 v[122:123], v[128:129], s[60:61] op_sel_hi:[1,0]
	v_pk_fma_f32 v[118:119], v[118:119], v[146:147], v[126:127]
	v_pk_mul_f32 v[124:125], v[124:125], s[60:61] op_sel_hi:[1,0]
	v_pk_fma_f32 v[114:115], v[114:115], v[142:143], v[122:123]
	v_pk_fma_f32 v[116:117], v[116:117], v[140:141], v[124:125]
	global_store_dwordx4 v[166:167], v[118:121], off offset:512
	global_store_dwordx4 v[166:167], v[114:117], off offset:528
	s_nop 1
	v_or_b32_e32 v114, 16, v160
	v_ashrrev_i32_e32 v115, 31, v114
	v_lshlrev_b64 v[114:115], 11, v[114:115]
	v_lshl_add_u64 v[118:119], v[114:115], 0, v[158:159]
	v_lshlrev_b64 v[120:121], 1, v[118:119]
	v_lshl_add_u64 v[114:115], s[50:51], 0, v[120:121]
	v_or_b32_e32 v120, 0x100, v120
	v_lshlrev_b32_e32 v122, 16, v188
	v_and_b32_e32 v123, 0xffff0000, v188
	v_lshlrev_b32_e32 v114, 16, v189
	v_and_b32_e32 v115, 0xffff0000, v189
	v_lshlrev_b32_e32 v124, 16, v190
	v_and_b32_e32 v125, 0xffff0000, v190
	v_pk_mul_f32 v[114:115], v[114:115], s[60:61] op_sel_hi:[1,0]
	v_lshlrev_b32_e32 v116, 16, v191
	v_and_b32_e32 v117, 0xffff0000, v191
	v_pk_mul_f32 v[122:123], v[122:123], s[60:61] op_sel_hi:[1,0]
	v_pk_fma_f32 v[112:113], v[112:113], v[152:153], v[114:115]
	v_pk_mul_f32 v[114:115], v[124:125], s[60:61] op_sel_hi:[1,0]
	v_pk_fma_f32 v[110:111], v[110:111], v[154:155], v[122:123]
	v_pk_mul_f32 v[116:117], v[116:117], s[60:61] op_sel_hi:[1,0]
	v_pk_fma_f32 v[106:107], v[106:107], v[150:151], v[114:115]
	v_lshl_add_u64 v[114:115], v[118:119], 2, s[36:37]
	v_pk_fma_f32 v[108:109], v[108:109], v[148:149], v[116:117]
	global_store_dwordx4 v[114:115], v[110:113], off
	global_store_dwordx4 v[114:115], v[106:109], off offset:16
	s_nop 1
	v_lshl_add_u64 v[106:107], s[50:51], 0, v[120:121]
	v_lshlrev_b32_e32 v110, 16, v192
	v_and_b32_e32 v111, 0xffff0000, v192
	v_lshlrev_b32_e32 v106, 16, v193
	v_and_b32_e32 v107, 0xffff0000, v193
	v_lshlrev_b32_e32 v112, 16, v194
	v_and_b32_e32 v113, 0xffff0000, v194
	v_pk_mul_f32 v[106:107], v[106:107], s[60:61] op_sel_hi:[1,0]
	v_lshlrev_b32_e32 v108, 16, v195
	v_and_b32_e32 v109, 0xffff0000, v195
	v_pk_mul_f32 v[110:111], v[110:111], s[60:61] op_sel_hi:[1,0]
	v_pk_fma_f32 v[104:105], v[104:105], v[144:145], v[106:107]
	v_pk_mul_f32 v[106:107], v[112:113], s[60:61] op_sel_hi:[1,0]
	v_pk_fma_f32 v[102:103], v[102:103], v[146:147], v[110:111]
	v_pk_mul_f32 v[108:109], v[108:109], s[60:61] op_sel_hi:[1,0]
	v_pk_fma_f32 v[98:99], v[98:99], v[142:143], v[106:107]
	v_pk_fma_f32 v[100:101], v[100:101], v[140:141], v[108:109]
	global_store_dwordx4 v[114:115], v[102:105], off offset:512
	global_store_dwordx4 v[114:115], v[98:101], off offset:528
	s_nop 1
	v_or_b32_e32 v98, 32, v160
	v_ashrrev_i32_e32 v99, 31, v98
	v_lshlrev_b64 v[98:99], 11, v[98:99]
	v_lshl_add_u64 v[102:103], v[98:99], 0, v[158:159]
	v_lshlrev_b64 v[104:105], 1, v[102:103]
	v_lshl_add_u64 v[98:99], s[50:51], 0, v[104:105]
	v_or_b32_e32 v104, 0x100, v104
	v_lshlrev_b32_e32 v106, 16, v196
	v_and_b32_e32 v107, 0xffff0000, v196
	v_lshlrev_b32_e32 v98, 16, v197
	v_and_b32_e32 v99, 0xffff0000, v197
	v_lshlrev_b32_e32 v108, 16, v198
	v_and_b32_e32 v109, 0xffff0000, v198
	v_pk_mul_f32 v[98:99], v[98:99], s[60:61] op_sel_hi:[1,0]
	v_lshlrev_b32_e32 v100, 16, v199
	v_and_b32_e32 v101, 0xffff0000, v199
	v_pk_mul_f32 v[106:107], v[106:107], s[60:61] op_sel_hi:[1,0]
	v_pk_fma_f32 v[96:97], v[96:97], v[152:153], v[98:99]
	v_pk_mul_f32 v[98:99], v[108:109], s[60:61] op_sel_hi:[1,0]
	v_pk_fma_f32 v[94:95], v[94:95], v[154:155], v[106:107]
	v_pk_mul_f32 v[100:101], v[100:101], s[60:61] op_sel_hi:[1,0]
	v_pk_fma_f32 v[90:91], v[90:91], v[150:151], v[98:99]
	v_lshl_add_u64 v[98:99], v[102:103], 2, s[36:37]
	v_pk_fma_f32 v[92:93], v[92:93], v[148:149], v[100:101]
	global_store_dwordx4 v[98:99], v[94:97], off
	global_store_dwordx4 v[98:99], v[90:93], off offset:16
	s_nop 1
	v_lshl_add_u64 v[90:91], s[50:51], 0, v[104:105]
	v_lshlrev_b32_e32 v94, 16, v200
	v_and_b32_e32 v95, 0xffff0000, v200
	v_lshlrev_b32_e32 v90, 16, v201
	v_and_b32_e32 v91, 0xffff0000, v201
	v_lshlrev_b32_e32 v96, 16, v202
	v_and_b32_e32 v97, 0xffff0000, v202
	v_pk_mul_f32 v[90:91], v[90:91], s[60:61] op_sel_hi:[1,0]
	v_lshlrev_b32_e32 v92, 16, v203
	v_and_b32_e32 v93, 0xffff0000, v203
	v_pk_mul_f32 v[94:95], v[94:95], s[60:61] op_sel_hi:[1,0]
	v_pk_fma_f32 v[88:89], v[88:89], v[144:145], v[90:91]
	v_pk_mul_f32 v[90:91], v[96:97], s[60:61] op_sel_hi:[1,0]
	v_pk_fma_f32 v[86:87], v[86:87], v[146:147], v[94:95]
	v_pk_mul_f32 v[92:93], v[92:93], s[60:61] op_sel_hi:[1,0]
	v_pk_fma_f32 v[82:83], v[82:83], v[142:143], v[90:91]
	v_pk_fma_f32 v[84:85], v[84:85], v[140:141], v[92:93]
	global_store_dwordx4 v[98:99], v[86:89], off offset:512
	global_store_dwordx4 v[98:99], v[82:85], off offset:528
	s_nop 1
	v_or_b32_e32 v82, 48, v160
	v_ashrrev_i32_e32 v83, 31, v82
	v_lshlrev_b64 v[82:83], 11, v[82:83]
	v_lshl_add_u64 v[86:87], v[82:83], 0, v[158:159]
	v_lshlrev_b64 v[88:89], 1, v[86:87]
	v_lshl_add_u64 v[82:83], s[50:51], 0, v[88:89]
	v_or_b32_e32 v88, 0x100, v88
	v_lshlrev_b32_e32 v90, 16, v204
	v_and_b32_e32 v91, 0xffff0000, v204
	v_lshlrev_b32_e32 v82, 16, v205
	v_and_b32_e32 v83, 0xffff0000, v205
	v_lshlrev_b32_e32 v92, 16, v206
	v_and_b32_e32 v93, 0xffff0000, v206
	v_pk_mul_f32 v[82:83], v[82:83], s[60:61] op_sel_hi:[1,0]
	v_lshlrev_b32_e32 v84, 16, v207
	v_and_b32_e32 v85, 0xffff0000, v207
	v_pk_mul_f32 v[90:91], v[90:91], s[60:61] op_sel_hi:[1,0]
	v_pk_fma_f32 v[80:81], v[80:81], v[152:153], v[82:83]
	v_pk_mul_f32 v[82:83], v[92:93], s[60:61] op_sel_hi:[1,0]
	v_pk_fma_f32 v[78:79], v[78:79], v[154:155], v[90:91]
	v_pk_mul_f32 v[84:85], v[84:85], s[60:61] op_sel_hi:[1,0]
	v_pk_fma_f32 v[74:75], v[74:75], v[150:151], v[82:83]
	v_lshl_add_u64 v[82:83], v[86:87], 2, s[36:37]
	v_pk_fma_f32 v[76:77], v[76:77], v[148:149], v[84:85]
	global_store_dwordx4 v[82:83], v[78:81], off
	global_store_dwordx4 v[82:83], v[74:77], off offset:16
	s_nop 1
	v_lshl_add_u64 v[74:75], s[50:51], 0, v[88:89]
	v_lshlrev_b32_e32 v78, 16, v218
	v_and_b32_e32 v79, 0xffff0000, v218
	v_lshlrev_b32_e32 v74, 16, v219
	v_and_b32_e32 v75, 0xffff0000, v219
	v_lshlrev_b32_e32 v80, 16, v220
	v_and_b32_e32 v81, 0xffff0000, v220
	v_lshlrev_b32_e32 v76, 16, v221
	v_and_b32_e32 v77, 0xffff0000, v221
	v_pk_mul_f32 v[78:79], v[78:79], s[60:61] op_sel_hi:[1,0]
	v_pk_mul_f32 v[74:75], v[74:75], s[60:61] op_sel_hi:[1,0]
	v_pk_fma_f32 v[70:71], v[70:71], v[146:147], v[78:79]
	v_pk_fma_f32 v[72:73], v[72:73], v[144:145], v[74:75]
	v_pk_mul_f32 v[74:75], v[80:81], s[60:61] op_sel_hi:[1,0]
	v_pk_mul_f32 v[76:77], v[76:77], s[60:61] op_sel_hi:[1,0]
	v_pk_fma_f32 v[66:67], v[66:67], v[142:143], v[74:75]
	v_pk_fma_f32 v[68:69], v[68:69], v[140:141], v[76:77]
	global_store_dwordx4 v[82:83], v[70:73], off offset:512
	global_store_dwordx4 v[82:83], v[66:69], off offset:528
	s_nop 0
	v_lshl_add_u64 v[70:71], v[156:157], 0, s[20:21]
	v_lshlrev_b64 v[72:73], 1, v[70:71]
	v_lshl_add_u64 v[66:67], s[50:51], 0, v[72:73]
	v_lshlrev_b32_e32 v184, 1, v156
	s_add_u32 s100, s50, 0x80000
	s_addc_u32 s101, s51, 0
	global_load_dwordx4 v[176:179], v184, s[100:101]
	global_load_dwordx4 v[180:183], v184, s[100:101] offset:256
	s_add_u32 s100, s100, 0x10000
	s_addc_u32 s101, s101, 0
	global_load_dwordx4 v[188:191], v184, s[100:101]
	global_load_dwordx4 v[192:195], v184, s[100:101] offset:256
	s_add_u32 s100, s100, 0x10000
	s_addc_u32 s101, s101, 0
	global_load_dwordx4 v[196:199], v184, s[100:101]
	global_load_dwordx4 v[200:203], v184, s[100:101] offset:256
	s_add_u32 s100, s100, 0x10000
	s_addc_u32 s101, s101, 0
	global_load_dwordx4 v[204:207], v184, s[100:101]
	global_load_dwordx4 v[218:221], v184, s[100:101] offset:256
	s_waitcnt vmcnt(0)
	v_or_b32_e32 v72, 0x100, v72
	s_mov_b64 s[20:21], 0x48000
	v_lshlrev_b32_e32 v74, 16, v176
	v_and_b32_e32 v75, 0xffff0000, v176
	v_lshlrev_b32_e32 v66, 16, v177
	v_and_b32_e32 v67, 0xffff0000, v177
	v_lshlrev_b32_e32 v76, 16, v178
	v_and_b32_e32 v77, 0xffff0000, v178
	v_pk_mul_f32 v[66:67], v[66:67], s[60:61] op_sel_hi:[1,0]
	v_lshlrev_b32_e32 v68, 16, v179
	v_and_b32_e32 v69, 0xffff0000, v179
	v_pk_mul_f32 v[74:75], v[74:75], s[60:61] op_sel_hi:[1,0]
	v_pk_fma_f32 v[64:65], v[64:65], v[152:153], v[66:67]
	v_pk_mul_f32 v[66:67], v[76:77], s[60:61] op_sel_hi:[1,0]
	v_pk_fma_f32 v[62:63], v[62:63], v[154:155], v[74:75]
	v_pk_mul_f32 v[68:69], v[68:69], s[60:61] op_sel_hi:[1,0]
	v_pk_fma_f32 v[58:59], v[58:59], v[150:151], v[66:67]
	v_lshl_add_u64 v[66:67], v[70:71], 2, s[36:37]
	v_pk_fma_f32 v[60:61], v[60:61], v[148:149], v[68:69]
	global_store_dwordx4 v[66:67], v[62:65], off
	global_store_dwordx4 v[66:67], v[58:61], off offset:16
	s_nop 1
	v_lshl_add_u64 v[58:59], s[50:51], 0, v[72:73]
	v_lshlrev_b32_e32 v62, 16, v180
	v_and_b32_e32 v63, 0xffff0000, v180
	v_lshlrev_b32_e32 v58, 16, v181
	v_and_b32_e32 v59, 0xffff0000, v181
	v_lshlrev_b32_e32 v64, 16, v182
	v_and_b32_e32 v65, 0xffff0000, v182
	v_lshlrev_b32_e32 v60, 16, v183
	v_and_b32_e32 v61, 0xffff0000, v183
	v_pk_mul_f32 v[62:63], v[62:63], s[60:61] op_sel_hi:[1,0]
	v_pk_mul_f32 v[58:59], v[58:59], s[60:61] op_sel_hi:[1,0]
	v_pk_fma_f32 v[54:55], v[54:55], v[146:147], v[62:63]
	v_pk_fma_f32 v[56:57], v[56:57], v[144:145], v[58:59]
	v_pk_mul_f32 v[58:59], v[64:65], s[60:61] op_sel_hi:[1,0]
	v_pk_mul_f32 v[60:61], v[60:61], s[60:61] op_sel_hi:[1,0]
	v_pk_fma_f32 v[50:51], v[50:51], v[142:143], v[58:59]
	v_pk_fma_f32 v[52:53], v[52:53], v[140:141], v[60:61]
	global_store_dwordx4 v[66:67], v[54:57], off offset:512
	global_store_dwordx4 v[66:67], v[50:53], off offset:528
	s_nop 0
	v_lshl_add_u64 v[54:55], v[156:157], 0, s[20:21]
	v_lshlrev_b64 v[56:57], 1, v[54:55]
	v_lshl_add_u64 v[50:51], s[50:51], 0, v[56:57]
	v_or_b32_e32 v56, 0x100, v56
	s_mov_b64 s[20:21], 0x50000
	v_lshlrev_b32_e32 v58, 16, v188
	v_and_b32_e32 v59, 0xffff0000, v188
	v_lshlrev_b32_e32 v50, 16, v189
	v_and_b32_e32 v51, 0xffff0000, v189
	v_lshlrev_b32_e32 v60, 16, v190
	v_and_b32_e32 v61, 0xffff0000, v190
	v_pk_mul_f32 v[50:51], v[50:51], s[60:61] op_sel_hi:[1,0]
	v_lshlrev_b32_e32 v52, 16, v191
	v_and_b32_e32 v53, 0xffff0000, v191
	v_pk_mul_f32 v[58:59], v[58:59], s[60:61] op_sel_hi:[1,0]
	v_pk_fma_f32 v[48:49], v[48:49], v[152:153], v[50:51]
	v_pk_mul_f32 v[50:51], v[60:61], s[60:61] op_sel_hi:[1,0]
	v_pk_fma_f32 v[46:47], v[46:47], v[154:155], v[58:59]
	v_pk_mul_f32 v[52:53], v[52:53], s[60:61] op_sel_hi:[1,0]
	v_pk_fma_f32 v[42:43], v[42:43], v[150:151], v[50:51]
	v_lshl_add_u64 v[50:51], v[54:55], 2, s[36:37]
	v_pk_fma_f32 v[44:45], v[44:45], v[148:149], v[52:53]
	global_store_dwordx4 v[50:51], v[46:49], off
	global_store_dwordx4 v[50:51], v[42:45], off offset:16
	s_nop 1
	v_lshl_add_u64 v[42:43], s[50:51], 0, v[56:57]
	v_lshlrev_b32_e32 v46, 16, v192
	v_and_b32_e32 v47, 0xffff0000, v192
	v_lshlrev_b32_e32 v42, 16, v193
	v_and_b32_e32 v43, 0xffff0000, v193
	v_lshlrev_b32_e32 v48, 16, v194
	v_and_b32_e32 v49, 0xffff0000, v194
	v_lshlrev_b32_e32 v44, 16, v195
	v_and_b32_e32 v45, 0xffff0000, v195
	v_pk_mul_f32 v[46:47], v[46:47], s[60:61] op_sel_hi:[1,0]
	v_pk_mul_f32 v[42:43], v[42:43], s[60:61] op_sel_hi:[1,0]
	v_pk_fma_f32 v[38:39], v[38:39], v[146:147], v[46:47]
	v_pk_fma_f32 v[40:41], v[40:41], v[144:145], v[42:43]
	v_pk_mul_f32 v[42:43], v[48:49], s[60:61] op_sel_hi:[1,0]
	v_pk_mul_f32 v[44:45], v[44:45], s[60:61] op_sel_hi:[1,0]
	v_pk_fma_f32 v[34:35], v[34:35], v[142:143], v[42:43]
	v_pk_fma_f32 v[36:37], v[36:37], v[140:141], v[44:45]
	global_store_dwordx4 v[50:51], v[38:41], off offset:512
	global_store_dwordx4 v[50:51], v[34:37], off offset:528
	s_nop 0
	v_lshl_add_u64 v[38:39], v[156:157], 0, s[20:21]
	v_lshlrev_b64 v[40:41], 1, v[38:39]
	v_lshl_add_u64 v[34:35], s[50:51], 0, v[40:41]
	v_or_b32_e32 v40, 0x100, v40
	s_mov_b64 s[20:21], 0x58000
	v_lshlrev_b32_e32 v42, 16, v196
	v_and_b32_e32 v43, 0xffff0000, v196
	v_lshlrev_b32_e32 v34, 16, v197
	v_and_b32_e32 v35, 0xffff0000, v197
	v_lshlrev_b32_e32 v44, 16, v198
	v_and_b32_e32 v45, 0xffff0000, v198
	v_pk_mul_f32 v[34:35], v[34:35], s[60:61] op_sel_hi:[1,0]
	v_lshlrev_b32_e32 v36, 16, v199
	v_and_b32_e32 v37, 0xffff0000, v199
	v_pk_mul_f32 v[42:43], v[42:43], s[60:61] op_sel_hi:[1,0]
	v_pk_fma_f32 v[32:33], v[32:33], v[152:153], v[34:35]
	v_pk_mul_f32 v[34:35], v[44:45], s[60:61] op_sel_hi:[1,0]
	v_pk_fma_f32 v[30:31], v[30:31], v[154:155], v[42:43]
	v_pk_mul_f32 v[36:37], v[36:37], s[60:61] op_sel_hi:[1,0]
	v_pk_fma_f32 v[26:27], v[26:27], v[150:151], v[34:35]
	v_lshl_add_u64 v[34:35], v[38:39], 2, s[36:37]
	v_pk_fma_f32 v[28:29], v[28:29], v[148:149], v[36:37]
	global_store_dwordx4 v[34:35], v[30:33], off
	global_store_dwordx4 v[34:35], v[26:29], off offset:16
	s_nop 1
	v_lshl_add_u64 v[26:27], s[50:51], 0, v[40:41]
	v_lshlrev_b32_e32 v30, 16, v200
	v_and_b32_e32 v31, 0xffff0000, v200
	v_lshlrev_b32_e32 v26, 16, v201
	v_and_b32_e32 v27, 0xffff0000, v201
	v_lshlrev_b32_e32 v32, 16, v202
	v_and_b32_e32 v33, 0xffff0000, v202
	v_lshlrev_b32_e32 v28, 16, v203
	v_and_b32_e32 v29, 0xffff0000, v203
	v_pk_mul_f32 v[30:31], v[30:31], s[60:61] op_sel_hi:[1,0]
	v_pk_mul_f32 v[26:27], v[26:27], s[60:61] op_sel_hi:[1,0]
	v_pk_fma_f32 v[22:23], v[22:23], v[146:147], v[30:31]
	v_pk_fma_f32 v[24:25], v[24:25], v[144:145], v[26:27]
	v_pk_mul_f32 v[26:27], v[32:33], s[60:61] op_sel_hi:[1,0]
	v_pk_mul_f32 v[28:29], v[28:29], s[60:61] op_sel_hi:[1,0]
	v_pk_fma_f32 v[18:19], v[18:19], v[142:143], v[26:27]
	v_pk_fma_f32 v[20:21], v[20:21], v[140:141], v[28:29]
	global_store_dwordx4 v[34:35], v[22:25], off offset:512
	global_store_dwordx4 v[34:35], v[18:21], off offset:528
	s_nop 0
	v_lshl_add_u64 v[22:23], v[156:157], 0, s[20:21]
	v_lshlrev_b64 v[24:25], 1, v[22:23]
	v_lshl_add_u64 v[18:19], s[50:51], 0, v[24:25]
	v_or_b32_e32 v24, 0x100, v24
	s_mov_b64 s[20:21], -1
	v_lshlrev_b32_e32 v26, 16, v204
	v_and_b32_e32 v27, 0xffff0000, v204
	v_lshlrev_b32_e32 v18, 16, v205
	v_and_b32_e32 v19, 0xffff0000, v205
	v_lshlrev_b32_e32 v28, 16, v206
	v_and_b32_e32 v29, 0xffff0000, v206
	v_pk_mul_f32 v[18:19], v[18:19], s[60:61] op_sel_hi:[1,0]
	v_lshlrev_b32_e32 v20, 16, v207
	v_and_b32_e32 v21, 0xffff0000, v207
	v_pk_mul_f32 v[26:27], v[26:27], s[60:61] op_sel_hi:[1,0]
	v_pk_fma_f32 v[16:17], v[16:17], v[152:153], v[18:19]
	v_pk_mul_f32 v[18:19], v[28:29], s[60:61] op_sel_hi:[1,0]
	v_pk_fma_f32 v[14:15], v[14:15], v[154:155], v[26:27]
	v_pk_mul_f32 v[20:21], v[20:21], s[60:61] op_sel_hi:[1,0]
	v_pk_fma_f32 v[10:11], v[10:11], v[150:151], v[18:19]
	v_lshl_add_u64 v[18:19], v[22:23], 2, s[36:37]
	v_pk_fma_f32 v[12:13], v[12:13], v[148:149], v[20:21]
	global_store_dwordx4 v[18:19], v[14:17], off
	global_store_dwordx4 v[18:19], v[10:13], off offset:16
	s_nop 1
	v_lshl_add_u64 v[10:11], s[50:51], 0, v[24:25]
	v_lshlrev_b32_e32 v14, 16, v218
	v_and_b32_e32 v15, 0xffff0000, v218
	v_lshlrev_b32_e32 v10, 16, v219
	v_and_b32_e32 v11, 0xffff0000, v219
	v_lshlrev_b32_e32 v16, 16, v220
	v_and_b32_e32 v17, 0xffff0000, v220
	v_lshlrev_b32_e32 v12, 16, v221
	v_and_b32_e32 v13, 0xffff0000, v221
	v_pk_mul_f32 v[14:15], v[14:15], s[60:61] op_sel_hi:[1,0]
	v_pk_mul_f32 v[10:11], v[10:11], s[60:61] op_sel_hi:[1,0]
	v_pk_fma_f32 v[6:7], v[6:7], v[146:147], v[14:15]
	v_pk_fma_f32 v[8:9], v[8:9], v[144:145], v[10:11]
	v_pk_mul_f32 v[10:11], v[16:17], s[60:61] op_sel_hi:[1,0]
	v_pk_mul_f32 v[12:13], v[12:13], s[60:61] op_sel_hi:[1,0]
	v_pk_fma_f32 v[2:3], v[2:3], v[142:143], v[10:11]
	v_pk_fma_f32 v[4:5], v[4:5], v[140:141], v[12:13]
	global_store_dwordx4 v[18:19], v[6:9], off offset:512
	global_store_dwordx4 v[18:19], v[2:5], off offset:528
	s_cbranch_vccnz .LBB0_1016
	s_andn2_b64 vcc, exec, s[8:9]
	s_cbranch_vccnz .LBB0_1015
	s_barrier
	s_branch .LBB0_1015

.LBB0_1049:
	v_lshl_or_b32 v160, s40, 8, v164
	v_ashrrev_i32_e32 v161, 31, v160
	v_lshl_add_u64 v[166:167], v[160:161], 2, s[6:7]
	global_load_dwordx4 v[140:143], v[166:167], off offset:16
	global_load_dwordx4 v[144:147], v[166:167], off
	v_lshlrev_b64 v[160:161], 1, v[160:161]
	v_lshl_add_u32 v185, s35, 8, v162
	v_lshl_add_u32 v184, v185, 12, v160
	s_add_u32 s100, s50, 0x0
	s_addc_u32 s101, s51, 0
	global_load_dwordx4 v[176:179], v184, s[100:101]
	global_load_dwordx4 v[180:183], v184, s[100:101] offset:256
	s_add_u32 s100, s100, 0x10000
	s_addc_u32 s101, s101, 0
	global_load_dwordx4 v[188:191], v184, s[100:101]
	global_load_dwordx4 v[192:195], v184, s[100:101] offset:256
	s_add_u32 s100, s100, 0x10000
	s_addc_u32 s101, s101, 0
	global_load_dwordx4 v[196:199], v184, s[100:101]
	global_load_dwordx4 v[200:203], v184, s[100:101] offset:256
	s_add_u32 s100, s100, 0x10000
	s_addc_u32 s101, s101, 0
	global_load_dwordx4 v[204:207], v184, s[100:101]
	global_load_dwordx4 v[218:221], v184, s[100:101] offset:256
	s_mov_b32 s3, 0x80000
	s_mov_b64 s[18:19], 0x80000
	s_mov_b32 s42, 0xc000
	s_waitcnt vmcnt(0)
	v_pk_add_f32 v[148:149], v[142:143], 1.0 op_sel_hi:[1,0]
	v_pk_add_f32 v[150:151], v[140:141], 1.0 op_sel_hi:[1,0]
	global_load_dwordx4 v[156:159], v[166:167], off offset:528
	global_load_dwordx4 v[140:143], v[166:167], off offset:512
	v_pk_add_f32 v[152:153], v[146:147], 1.0 op_sel_hi:[1,0]
	v_pk_add_f32 v[154:155], v[144:145], 1.0 op_sel_hi:[1,0]
	s_waitcnt vmcnt(0)
	v_pk_add_f32 v[146:147], v[140:141], 1.0 op_sel_hi:[1,0]
	v_pk_add_f32 v[140:141], v[158:159], 1.0 op_sel_hi:[1,0]
	v_lshl_add_u32 v158, s35, 8, v162
	v_ashrrev_i32_e32 v159, 31, v158
	v_pk_add_f32 v[144:145], v[142:143], 1.0 op_sel_hi:[1,0]
	v_pk_add_f32 v[142:143], v[156:157], 1.0 op_sel_hi:[1,0]
	v_lshlrev_b64 v[156:157], 12, v[158:159]
	v_lshl_add_u64 v[156:157], s[50:51], 0, v[156:157]
	v_lshl_add_u64 v[156:157], v[156:157], 0, v[160:161]
	v_lshlrev_b32_e32 v170, 16, v176
	v_and_b32_e32 v171, 0xffff0000, v176
	v_lshlrev_b32_e32 v166, 16, v177
	v_and_b32_e32 v167, 0xffff0000, v177
	v_lshlrev_b32_e32 v172, 16, v178
	v_and_b32_e32 v173, 0xffff0000, v178
	v_lshlrev_b32_e32 v168, 16, v179
	v_and_b32_e32 v169, 0xffff0000, v179
	v_pk_mul_f32 v[166:167], v[166:167], s[60:61] op_sel_hi:[1,0]
	v_pk_mul_f32 v[170:171], v[170:171], s[60:61] op_sel_hi:[1,0]
	v_pk_fma_f32 v[128:129], v[128:129], v[152:153], v[166:167]
	v_pk_mul_f32 v[166:167], v[172:173], s[60:61] op_sel_hi:[1,0]
	v_pk_mul_f32 v[168:169], v[168:169], s[60:61] op_sel_hi:[1,0]
	v_pk_fma_f32 v[126:127], v[126:127], v[154:155], v[170:171]
	v_pk_fma_f32 v[168:169], v[124:125], v[148:149], v[168:169]
	v_pk_fma_f32 v[124:125], v[122:123], v[150:151], v[166:167]
	v_cvt_pk_bf16_f32 v122, v126, v127
	v_cvt_pk_bf16_f32 v123, v128, v129
	v_cvt_pk_bf16_f32 v124, v124, v125
	v_cvt_pk_bf16_f32 v125, v168, v169
	global_store_dwordx4 v[156:157], v[122:125], off
	v_lshlrev_b32_e32 v126, 16, v180
	v_and_b32_e32 v127, 0xffff0000, v180
	v_lshlrev_b32_e32 v122, 16, v181
	v_and_b32_e32 v123, 0xffff0000, v181
	v_lshlrev_b32_e32 v128, 16, v182
	v_and_b32_e32 v129, 0xffff0000, v182
	v_lshlrev_b32_e32 v124, 16, v183
	v_and_b32_e32 v125, 0xffff0000, v183
	v_pk_mul_f32 v[122:123], v[122:123], s[60:61] op_sel_hi:[1,0]
	v_pk_mul_f32 v[126:127], v[126:127], s[60:61] op_sel_hi:[1,0]
	v_pk_fma_f32 v[120:121], v[120:121], v[144:145], v[122:123]
	v_pk_mul_f32 v[122:123], v[128:129], s[60:61] op_sel_hi:[1,0]
	v_pk_mul_f32 v[124:125], v[124:125], s[60:61] op_sel_hi:[1,0]
	v_pk_fma_f32 v[118:119], v[118:119], v[146:147], v[126:127]
	v_pk_fma_f32 v[124:125], v[116:117], v[140:141], v[124:125]
	v_pk_fma_f32 v[116:117], v[114:115], v[142:143], v[122:123]
	v_cvt_pk_bf16_f32 v114, v118, v119
	v_cvt_pk_bf16_f32 v115, v120, v121
	v_cvt_pk_bf16_f32 v116, v116, v117
	v_cvt_pk_bf16_f32 v117, v124, v125
	global_store_dwordx4 v[156:157], v[114:117], off offset:256
	s_nop 1
	v_or_b32_e32 v114, 16, v158
	v_ashrrev_i32_e32 v115, 31, v114
	v_lshlrev_b64 v[114:115], 12, v[114:115]
	v_lshl_add_u64 v[114:115], s[50:51], 0, v[114:115]
	v_lshl_add_u64 v[118:119], v[114:115], 0, v[160:161]
	v_lshlrev_b32_e32 v120, 16, v188
	v_and_b32_e32 v121, 0xffff0000, v188
	v_lshlrev_b32_e32 v114, 16, v189
	v_and_b32_e32 v115, 0xffff0000, v189
	v_lshlrev_b32_e32 v122, 16, v190
	v_and_b32_e32 v123, 0xffff0000, v190
	v_lshlrev_b32_e32 v116, 16, v191
	v_and_b32_e32 v117, 0xffff0000, v191
	v_pk_mul_f32 v[114:115], v[114:115], s[60:61] op_sel_hi:[1,0]
	v_pk_mul_f32 v[120:121], v[120:121], s[60:61] op_sel_hi:[1,0]
	v_pk_fma_f32 v[112:113], v[112:113], v[152:153], v[114:115]
	v_pk_mul_f32 v[114:115], v[122:123], s[60:61] op_sel_hi:[1,0]
	v_pk_mul_f32 v[116:117], v[116:117], s[60:61] op_sel_hi:[1,0]
	v_pk_fma_f32 v[110:111], v[110:111], v[154:155], v[120:121]
	v_pk_fma_f32 v[116:117], v[108:109], v[148:149], v[116:117]
	v_pk_fma_f32 v[108:109], v[106:107], v[150:151], v[114:115]
	v_cvt_pk_bf16_f32 v106, v110, v111
	v_cvt_pk_bf16_f32 v107, v112, v113
	v_cvt_pk_bf16_f32 v108, v108, v109
	v_cvt_pk_bf16_f32 v109, v116, v117
	global_store_dwordx4 v[118:119], v[106:109], off
	v_lshlrev_b32_e32 v110, 16, v192
	v_and_b32_e32 v111, 0xffff0000, v192
	v_lshlrev_b32_e32 v106, 16, v193
	v_and_b32_e32 v107, 0xffff0000, v193
	v_lshlrev_b32_e32 v112, 16, v194
	v_and_b32_e32 v113, 0xffff0000, v194
	v_lshlrev_b32_e32 v108, 16, v195
	v_and_b32_e32 v109, 0xffff0000, v195
	v_pk_mul_f32 v[106:107], v[106:107], s[60:61] op_sel_hi:[1,0]
	v_pk_mul_f32 v[110:111], v[110:111], s[60:61] op_sel_hi:[1,0]
	v_pk_fma_f32 v[104:105], v[104:105], v[144:145], v[106:107]
	v_pk_mul_f32 v[106:107], v[112:113], s[60:61] op_sel_hi:[1,0]
	v_pk_mul_f32 v[108:109], v[108:109], s[60:61] op_sel_hi:[1,0]
	v_pk_fma_f32 v[102:103], v[102:103], v[146:147], v[110:111]
	v_pk_fma_f32 v[108:109], v[100:101], v[140:141], v[108:109]
	v_pk_fma_f32 v[100:101], v[98:99], v[142:143], v[106:107]
	v_cvt_pk_bf16_f32 v98, v102, v103
	v_cvt_pk_bf16_f32 v99, v104, v105
	v_cvt_pk_bf16_f32 v100, v100, v101
	v_cvt_pk_bf16_f32 v101, v108, v109
	global_store_dwordx4 v[118:119], v[98:101], off offset:256
	s_nop 1
	v_or_b32_e32 v98, 32, v158
	v_ashrrev_i32_e32 v99, 31, v98
	v_lshlrev_b64 v[98:99], 12, v[98:99]
	v_lshl_add_u64 v[98:99], s[50:51], 0, v[98:99]
	v_lshl_add_u64 v[102:103], v[98:99], 0, v[160:161]
	v_lshlrev_b32_e32 v104, 16, v196
	v_and_b32_e32 v105, 0xffff0000, v196
	v_lshlrev_b32_e32 v98, 16, v197
	v_and_b32_e32 v99, 0xffff0000, v197
	v_lshlrev_b32_e32 v106, 16, v198
	v_and_b32_e32 v107, 0xffff0000, v198
	v_lshlrev_b32_e32 v100, 16, v199
	v_and_b32_e32 v101, 0xffff0000, v199
	v_pk_mul_f32 v[98:99], v[98:99], s[60:61] op_sel_hi:[1,0]
	v_pk_mul_f32 v[104:105], v[104:105], s[60:61] op_sel_hi:[1,0]
	v_pk_fma_f32 v[96:97], v[96:97], v[152:153], v[98:99]
	v_pk_mul_f32 v[98:99], v[106:107], s[60:61] op_sel_hi:[1,0]
	v_pk_mul_f32 v[100:101], v[100:101], s[60:61] op_sel_hi:[1,0]
	v_pk_fma_f32 v[94:95], v[94:95], v[154:155], v[104:105]
	v_pk_fma_f32 v[100:101], v[92:93], v[148:149], v[100:101]
	v_pk_fma_f32 v[92:93], v[90:91], v[150:151], v[98:99]
	v_cvt_pk_bf16_f32 v90, v94, v95
	v_cvt_pk_bf16_f32 v91, v96, v97
	v_cvt_pk_bf16_f32 v92, v92, v93
	v_cvt_pk_bf16_f32 v93, v100, v101
	global_store_dwordx4 v[102:103], v[90:93], off
	v_lshlrev_b32_e32 v94, 16, v200
	v_and_b32_e32 v95, 0xffff0000, v200
	v_lshlrev_b32_e32 v90, 16, v201
	v_and_b32_e32 v91, 0xffff0000, v201
	v_lshlrev_b32_e32 v96, 16, v202
	v_and_b32_e32 v97, 0xffff0000, v202
	v_lshlrev_b32_e32 v92, 16, v203
	v_and_b32_e32 v93, 0xffff0000, v203
	v_pk_mul_f32 v[90:91], v[90:91], s[60:61] op_sel_hi:[1,0]
	v_pk_mul_f32 v[94:95], v[94:95], s[60:61] op_sel_hi:[1,0]
	v_pk_fma_f32 v[88:89], v[88:89], v[144:145], v[90:91]
	v_pk_mul_f32 v[90:91], v[96:97], s[60:61] op_sel_hi:[1,0]
	v_pk_mul_f32 v[92:93], v[92:93], s[60:61] op_sel_hi:[1,0]
	v_pk_fma_f32 v[86:87], v[86:87], v[146:147], v[94:95]
	v_pk_fma_f32 v[92:93], v[84:85], v[140:141], v[92:93]
	v_pk_fma_f32 v[84:85], v[82:83], v[142:143], v[90:91]
	v_cvt_pk_bf16_f32 v82, v86, v87
	v_cvt_pk_bf16_f32 v83, v88, v89
	v_cvt_pk_bf16_f32 v84, v84, v85
	v_cvt_pk_bf16_f32 v85, v92, v93
	global_store_dwordx4 v[102:103], v[82:85], off offset:256
	s_nop 1
	v_or_b32_e32 v82, 48, v158
	v_ashrrev_i32_e32 v83, 31, v82
	v_lshlrev_b64 v[82:83], 12, v[82:83]
	v_lshl_add_u64 v[82:83], s[50:51], 0, v[82:83]
	v_lshl_add_u64 v[86:87], v[82:83], 0, v[160:161]
	v_lshlrev_b32_e32 v88, 16, v204
	v_and_b32_e32 v89, 0xffff0000, v204
	v_lshlrev_b32_e32 v82, 16, v205
	v_and_b32_e32 v83, 0xffff0000, v205
	v_lshlrev_b32_e32 v90, 16, v206
	v_and_b32_e32 v91, 0xffff0000, v206
	v_lshlrev_b32_e32 v84, 16, v207
	v_and_b32_e32 v85, 0xffff0000, v207
	v_pk_mul_f32 v[82:83], v[82:83], s[60:61] op_sel_hi:[1,0]
	v_pk_mul_f32 v[88:89], v[88:89], s[60:61] op_sel_hi:[1,0]
	v_pk_fma_f32 v[80:81], v[80:81], v[152:153], v[82:83]
	v_pk_mul_f32 v[82:83], v[90:91], s[60:61] op_sel_hi:[1,0]
	v_pk_mul_f32 v[84:85], v[84:85], s[60:61] op_sel_hi:[1,0]
	v_pk_fma_f32 v[78:79], v[78:79], v[154:155], v[88:89]
	v_pk_fma_f32 v[84:85], v[76:77], v[148:149], v[84:85]
	v_pk_fma_f32 v[76:77], v[74:75], v[150:151], v[82:83]
	v_cvt_pk_bf16_f32 v74, v78, v79
	v_cvt_pk_bf16_f32 v75, v80, v81
	v_cvt_pk_bf16_f32 v76, v76, v77
	v_cvt_pk_bf16_f32 v77, v84, v85
	global_store_dwordx4 v[86:87], v[74:77], off
	v_lshlrev_b32_e32 v78, 16, v218
	v_and_b32_e32 v79, 0xffff0000, v218
	v_lshlrev_b32_e32 v74, 16, v219
	v_and_b32_e32 v75, 0xffff0000, v219
	v_lshlrev_b32_e32 v80, 16, v220
	v_and_b32_e32 v81, 0xffff0000, v220
	v_lshlrev_b32_e32 v76, 16, v221
	v_and_b32_e32 v77, 0xffff0000, v221
	v_pk_mul_f32 v[74:75], v[74:75], s[60:61] op_sel_hi:[1,0]
	v_pk_mul_f32 v[78:79], v[78:79], s[60:61] op_sel_hi:[1,0]
	v_pk_fma_f32 v[72:73], v[72:73], v[144:145], v[74:75]
	v_pk_mul_f32 v[74:75], v[80:81], s[60:61] op_sel_hi:[1,0]
	v_pk_mul_f32 v[76:77], v[76:77], s[60:61] op_sel_hi:[1,0]
	v_pk_fma_f32 v[70:71], v[70:71], v[146:147], v[78:79]
	v_pk_fma_f32 v[76:77], v[68:69], v[140:141], v[76:77]
	v_pk_fma_f32 v[68:69], v[66:67], v[142:143], v[74:75]
	v_cvt_pk_bf16_f32 v67, v72, v73
	v_add_co_u32_e32 v72, vcc, s3, v156
	v_cvt_pk_bf16_f32 v66, v70, v71
	v_cvt_pk_bf16_f32 v68, v68, v69
	v_cvt_pk_bf16_f32 v69, v76, v77
	v_addc_co_u32_e32 v73, vcc, 0, v157, vcc
	global_store_dwordx4 v[86:87], v[66:69], off offset:256
	v_lshl_add_u32 v184, v158, 12, v160
	s_add_u32 s100, s50, 0x80000
	s_addc_u32 s101, s51, 0
	global_load_dwordx4 v[176:179], v184, s[100:101]
	global_load_dwordx4 v[180:183], v184, s[100:101] offset:256
	s_add_u32 s100, s100, 0x10000
	s_addc_u32 s101, s101, 0
	global_load_dwordx4 v[188:191], v184, s[100:101]
	global_load_dwordx4 v[192:195], v184, s[100:101] offset:256
	s_add_u32 s100, s100, 0x10000
	s_addc_u32 s101, s101, 0
	global_load_dwordx4 v[196:199], v184, s[100:101]
	global_load_dwordx4 v[200:203], v184, s[100:101] offset:256
	s_add_u32 s100, s100, 0x10000
	s_addc_u32 s101, s101, 0
	global_load_dwordx4 v[204:207], v184, s[100:101]
	global_load_dwordx4 v[218:221], v184, s[100:101] offset:256
	s_waitcnt vmcnt(0)
	s_mov_b32 s3, 0x90000
	v_lshl_add_u64 v[66:67], v[156:157], 0, s[18:19]
	s_mov_b64 s[18:19], 0x90000
	v_lshlrev_b32_e32 v74, 16, v176
	v_and_b32_e32 v75, 0xffff0000, v176
	v_lshlrev_b32_e32 v68, 16, v177
	v_and_b32_e32 v69, 0xffff0000, v177
	v_lshlrev_b32_e32 v76, 16, v178
	v_and_b32_e32 v77, 0xffff0000, v178
	v_lshlrev_b32_e32 v70, 16, v179
	v_and_b32_e32 v71, 0xffff0000, v179
	v_pk_mul_f32 v[68:69], v[68:69], s[60:61] op_sel_hi:[1,0]
	v_pk_mul_f32 v[74:75], v[74:75], s[60:61] op_sel_hi:[1,0]
	v_pk_fma_f32 v[64:65], v[64:65], v[152:153], v[68:69]
	v_pk_mul_f32 v[68:69], v[76:77], s[60:61] op_sel_hi:[1,0]
	v_pk_mul_f32 v[70:71], v[70:71], s[60:61] op_sel_hi:[1,0]
	v_pk_fma_f32 v[62:63], v[62:63], v[154:155], v[74:75]
	v_pk_fma_f32 v[70:71], v[60:61], v[148:149], v[70:71]
	v_pk_fma_f32 v[60:61], v[58:59], v[150:151], v[68:69]
	v_cvt_pk_bf16_f32 v58, v62, v63
	v_cvt_pk_bf16_f32 v59, v64, v65
	v_cvt_pk_bf16_f32 v60, v60, v61
	v_cvt_pk_bf16_f32 v61, v70, v71
	global_store_dwordx4 v[72:73], v[58:61], off
	v_lshlrev_b32_e32 v62, 16, v180
	v_and_b32_e32 v63, 0xffff0000, v180
	v_lshlrev_b32_e32 v58, 16, v181
	v_and_b32_e32 v59, 0xffff0000, v181
	v_lshlrev_b32_e32 v64, 16, v182
	v_and_b32_e32 v65, 0xffff0000, v182
	v_lshlrev_b32_e32 v60, 16, v183
	v_and_b32_e32 v61, 0xffff0000, v183
	v_pk_mul_f32 v[58:59], v[58:59], s[60:61] op_sel_hi:[1,0]
	v_pk_mul_f32 v[62:63], v[62:63], s[60:61] op_sel_hi:[1,0]
	v_pk_fma_f32 v[56:57], v[56:57], v[144:145], v[58:59]
	v_pk_mul_f32 v[58:59], v[64:65], s[60:61] op_sel_hi:[1,0]
	v_pk_mul_f32 v[60:61], v[60:61], s[60:61] op_sel_hi:[1,0]
	v_pk_fma_f32 v[54:55], v[54:55], v[146:147], v[62:63]
	v_pk_fma_f32 v[60:61], v[52:53], v[140:141], v[60:61]
	v_pk_fma_f32 v[52:53], v[50:51], v[142:143], v[58:59]
	v_cvt_pk_bf16_f32 v51, v56, v57
	v_add_co_u32_e32 v56, vcc, s3, v156
	v_cvt_pk_bf16_f32 v50, v54, v55
	v_cvt_pk_bf16_f32 v52, v52, v53
	v_cvt_pk_bf16_f32 v53, v60, v61
	v_addc_co_u32_e32 v57, vcc, 0, v157, vcc
	global_store_dwordx4 v[66:67], v[50:53], off offset:256
	s_nop 0
	s_mov_b32 s3, 0xa0000
	v_lshl_add_u64 v[50:51], v[156:157], 0, s[18:19]
	s_mov_b64 s[18:19], 0xa0000
	v_lshlrev_b32_e32 v58, 16, v188
	v_and_b32_e32 v59, 0xffff0000, v188
	v_lshlrev_b32_e32 v52, 16, v189
	v_and_b32_e32 v53, 0xffff0000, v189
	v_lshlrev_b32_e32 v60, 16, v190
	v_and_b32_e32 v61, 0xffff0000, v190
	v_lshlrev_b32_e32 v54, 16, v191
	v_and_b32_e32 v55, 0xffff0000, v191
	v_pk_mul_f32 v[52:53], v[52:53], s[60:61] op_sel_hi:[1,0]
	v_pk_mul_f32 v[58:59], v[58:59], s[60:61] op_sel_hi:[1,0]
	v_pk_fma_f32 v[48:49], v[48:49], v[152:153], v[52:53]
	v_pk_mul_f32 v[52:53], v[60:61], s[60:61] op_sel_hi:[1,0]
	v_pk_mul_f32 v[54:55], v[54:55], s[60:61] op_sel_hi:[1,0]
	v_pk_fma_f32 v[46:47], v[46:47], v[154:155], v[58:59]
	v_pk_fma_f32 v[54:55], v[44:45], v[148:149], v[54:55]
	v_pk_fma_f32 v[44:45], v[42:43], v[150:151], v[52:53]
	v_cvt_pk_bf16_f32 v42, v46, v47
	v_cvt_pk_bf16_f32 v43, v48, v49
	v_cvt_pk_bf16_f32 v44, v44, v45
	v_cvt_pk_bf16_f32 v45, v54, v55
	global_store_dwordx4 v[56:57], v[42:45], off
	v_lshlrev_b32_e32 v46, 16, v192
	v_and_b32_e32 v47, 0xffff0000, v192
	v_lshlrev_b32_e32 v42, 16, v193
	v_and_b32_e32 v43, 0xffff0000, v193
	v_lshlrev_b32_e32 v48, 16, v194
	v_and_b32_e32 v49, 0xffff0000, v194
	v_lshlrev_b32_e32 v44, 16, v195
	v_and_b32_e32 v45, 0xffff0000, v195
	v_pk_mul_f32 v[42:43], v[42:43], s[60:61] op_sel_hi:[1,0]
	v_pk_mul_f32 v[46:47], v[46:47], s[60:61] op_sel_hi:[1,0]
	v_pk_fma_f32 v[40:41], v[40:41], v[144:145], v[42:43]
	v_pk_mul_f32 v[42:43], v[48:49], s[60:61] op_sel_hi:[1,0]
	v_pk_mul_f32 v[44:45], v[44:45], s[60:61] op_sel_hi:[1,0]
	v_pk_fma_f32 v[38:39], v[38:39], v[146:147], v[46:47]
	v_pk_fma_f32 v[44:45], v[36:37], v[140:141], v[44:45]
	v_pk_fma_f32 v[36:37], v[34:35], v[142:143], v[42:43]
	v_cvt_pk_bf16_f32 v35, v40, v41
	v_add_co_u32_e32 v40, vcc, s3, v156
	v_cvt_pk_bf16_f32 v34, v38, v39
	v_cvt_pk_bf16_f32 v36, v36, v37
	v_cvt_pk_bf16_f32 v37, v44, v45
	v_addc_co_u32_e32 v41, vcc, 0, v157, vcc
	global_store_dwordx4 v[50:51], v[34:37], off offset:256
	s_nop 0
	s_mov_b32 s3, 0xb0000
	v_lshl_add_u64 v[34:35], v[156:157], 0, s[18:19]
	s_mov_b64 s[18:19], 0xb0000
	v_lshlrev_b32_e32 v42, 16, v196
	v_and_b32_e32 v43, 0xffff0000, v196
	v_lshlrev_b32_e32 v36, 16, v197
	v_and_b32_e32 v37, 0xffff0000, v197
	v_lshlrev_b32_e32 v44, 16, v198
	v_and_b32_e32 v45, 0xffff0000, v198
	v_lshlrev_b32_e32 v38, 16, v199
	v_and_b32_e32 v39, 0xffff0000, v199
	v_pk_mul_f32 v[36:37], v[36:37], s[60:61] op_sel_hi:[1,0]
	v_pk_mul_f32 v[42:43], v[42:43], s[60:61] op_sel_hi:[1,0]
	v_pk_fma_f32 v[32:33], v[32:33], v[152:153], v[36:37]
	v_pk_mul_f32 v[36:37], v[44:45], s[60:61] op_sel_hi:[1,0]
	v_pk_mul_f32 v[38:39], v[38:39], s[60:61] op_sel_hi:[1,0]
	v_pk_fma_f32 v[30:31], v[30:31], v[154:155], v[42:43]
	v_pk_fma_f32 v[38:39], v[28:29], v[148:149], v[38:39]
	v_pk_fma_f32 v[28:29], v[26:27], v[150:151], v[36:37]
	v_cvt_pk_bf16_f32 v26, v30, v31
	v_cvt_pk_bf16_f32 v27, v32, v33
	v_cvt_pk_bf16_f32 v28, v28, v29
	v_cvt_pk_bf16_f32 v29, v38, v39
	global_store_dwordx4 v[40:41], v[26:29], off
	v_lshlrev_b32_e32 v30, 16, v200
	v_and_b32_e32 v31, 0xffff0000, v200
	v_lshlrev_b32_e32 v26, 16, v201
	v_and_b32_e32 v27, 0xffff0000, v201
	v_lshlrev_b32_e32 v32, 16, v202
	v_and_b32_e32 v33, 0xffff0000, v202
	v_lshlrev_b32_e32 v28, 16, v203
	v_and_b32_e32 v29, 0xffff0000, v203
	v_pk_mul_f32 v[26:27], v[26:27], s[60:61] op_sel_hi:[1,0]
	v_pk_mul_f32 v[30:31], v[30:31], s[60:61] op_sel_hi:[1,0]
	v_pk_fma_f32 v[24:25], v[24:25], v[144:145], v[26:27]
	v_pk_mul_f32 v[26:27], v[32:33], s[60:61] op_sel_hi:[1,0]
	v_pk_mul_f32 v[28:29], v[28:29], s[60:61] op_sel_hi:[1,0]
	v_pk_fma_f32 v[22:23], v[22:23], v[146:147], v[30:31]
	v_pk_fma_f32 v[28:29], v[20:21], v[140:141], v[28:29]
	v_pk_fma_f32 v[20:21], v[18:19], v[142:143], v[26:27]
	v_cvt_pk_bf16_f32 v19, v24, v25
	v_add_co_u32_e32 v24, vcc, s3, v156
	v_cvt_pk_bf16_f32 v18, v22, v23
	v_cvt_pk_bf16_f32 v20, v20, v21
	v_cvt_pk_bf16_f32 v21, v28, v29
	v_addc_co_u32_e32 v25, vcc, 0, v157, vcc
	global_store_dwordx4 v[34:35], v[18:21], off offset:256
	s_nop 0
	s_andn2_b64 vcc, exec, s[0:1]
	v_lshl_add_u64 v[18:19], v[156:157], 0, s[18:19]
	s_mov_b64 s[18:19], -1
	v_lshlrev_b32_e32 v26, 16, v204
	v_and_b32_e32 v27, 0xffff0000, v204
	v_lshlrev_b32_e32 v20, 16, v205
	v_and_b32_e32 v21, 0xffff0000, v205
	v_lshlrev_b32_e32 v28, 16, v206
	v_and_b32_e32 v29, 0xffff0000, v206
	v_lshlrev_b32_e32 v22, 16, v207
	v_and_b32_e32 v23, 0xffff0000, v207
	v_pk_mul_f32 v[20:21], v[20:21], s[60:61] op_sel_hi:[1,0]
	v_pk_mul_f32 v[26:27], v[26:27], s[60:61] op_sel_hi:[1,0]
	v_pk_fma_f32 v[16:17], v[16:17], v[152:153], v[20:21]
	v_pk_mul_f32 v[20:21], v[28:29], s[60:61] op_sel_hi:[1,0]
	v_pk_mul_f32 v[22:23], v[22:23], s[60:61] op_sel_hi:[1,0]
	v_pk_fma_f32 v[14:15], v[14:15], v[154:155], v[26:27]
	v_pk_fma_f32 v[22:23], v[12:13], v[148:149], v[22:23]
	v_pk_fma_f32 v[12:13], v[10:11], v[150:151], v[20:21]
	v_cvt_pk_bf16_f32 v10, v14, v15
	v_cvt_pk_bf16_f32 v11, v16, v17
	v_cvt_pk_bf16_f32 v12, v12, v13
	v_cvt_pk_bf16_f32 v13, v22, v23
	global_store_dwordx4 v[24:25], v[10:13], off
	v_lshlrev_b32_e32 v14, 16, v218
	v_and_b32_e32 v15, 0xffff0000, v218
	v_lshlrev_b32_e32 v10, 16, v219
	v_and_b32_e32 v11, 0xffff0000, v219
	v_lshlrev_b32_e32 v16, 16, v220
	v_and_b32_e32 v17, 0xffff0000, v220
	v_lshlrev_b32_e32 v12, 16, v221
	v_and_b32_e32 v13, 0xffff0000, v221
	v_pk_mul_f32 v[10:11], v[10:11], s[60:61] op_sel_hi:[1,0]
	v_pk_mul_f32 v[14:15], v[14:15], s[60:61] op_sel_hi:[1,0]
	v_pk_fma_f32 v[8:9], v[8:9], v[144:145], v[10:11]
	v_pk_mul_f32 v[10:11], v[16:17], s[60:61] op_sel_hi:[1,0]
	v_pk_mul_f32 v[12:13], v[12:13], s[60:61] op_sel_hi:[1,0]
	v_pk_fma_f32 v[6:7], v[6:7], v[146:147], v[14:15]
	v_pk_fma_f32 v[12:13], v[4:5], v[140:141], v[12:13]
	v_pk_fma_f32 v[4:5], v[2:3], v[142:143], v[10:11]
	v_cvt_pk_bf16_f32 v2, v6, v7
	v_cvt_pk_bf16_f32 v3, v8, v9
	v_cvt_pk_bf16_f32 v4, v4, v5
	v_cvt_pk_bf16_f32 v5, v12, v13
	global_store_dwordx4 v[18:19], v[2:5], off offset:256
	s_cbranch_vccnz .LBB0_1038
	s_andn2_b64 vcc, exec, s[4:5]
	s_cbranch_vccnz .LBB0_1037
	s_barrier
	s_branch .LBB0_1037
